# v102 + counted vmcnt(6) in the MLA unit prologue: the q/rope loads are awaited without draining the tile-0/1 LDS-DMA pieces, rope math overlaps their flight
# baseline (speedup 1.0000x reference)
.LBB0_476:
	s_waitcnt vmcnt(6)
	v_lshlrev_b32_e32 v28, 16, v8
	v_and_b32_e32 v29, 0xffff0000, v8
	v_mov_b32_e32 v31, v26
	v_mov_b32_e32 v26, v25
	v_lshlrev_b32_e32 v6, 16, v12
	v_and_b32_e32 v7, 0xffff0000, v12
	v_mov_b32_e32 v30, v24
	v_pk_mul_f32 v[24:25], v[26:27], v[28:29]
	v_lshlrev_b32_e32 v8, 16, v9
	v_pk_fma_f32 v[24:25], v[30:31], v[6:7], v[24:25] neg_lo:[0,0,1] neg_hi:[0,0,1]
	v_and_b32_e32 v9, 0xffff0000, v9
	v_cvt_pk_bf16_f32 v90, v24, v25
	v_pk_mul_f32 v[24:25], v[30:31], v[28:29]
	v_mov_b32_e32 v12, v20
	v_pk_fma_f32 v[6:7], v[26:27], v[6:7], v[24:25]
	v_lshlrev_b32_e32 v133, 2, v38
	v_cvt_pk_bf16_f32 v94, v6, v7
	v_lshlrev_b32_e32 v6, 16, v13
	v_and_b32_e32 v7, 0xffff0000, v13
	v_mov_b32_e32 v13, v22
	v_mov_b32_e32 v22, v21
	v_pk_mul_f32 v[20:21], v[22:23], v[8:9]
	v_pk_mul_f32 v[8:9], v[12:13], v[8:9]
	v_pk_fma_f32 v[20:21], v[12:13], v[6:7], v[20:21] neg_lo:[0,0,1] neg_hi:[0,0,1]
	v_pk_fma_f32 v[6:7], v[22:23], v[6:7], v[8:9]
	v_lshlrev_b32_e32 v8, 16, v10
	v_and_b32_e32 v9, 0xffff0000, v10
	v_mov_b32_e32 v12, v16
	v_mov_b32_e32 v13, v18
	v_mov_b32_e32 v18, v17
	v_cvt_pk_bf16_f32 v95, v6, v7
	v_lshlrev_b32_e32 v6, 16, v14
	v_and_b32_e32 v7, 0xffff0000, v14
	v_pk_mul_f32 v[16:17], v[18:19], v[8:9]
	v_pk_mul_f32 v[8:9], v[12:13], v[8:9]
	v_pk_fma_f32 v[16:17], v[12:13], v[6:7], v[16:17] neg_lo:[0,0,1] neg_hi:[0,0,1]
	v_pk_fma_f32 v[6:7], v[18:19], v[6:7], v[8:9]
	v_lshlrev_b32_e32 v8, 16, v11
	v_and_b32_e32 v9, 0xffff0000, v11
	v_mov_b32_e32 v11, v4
	v_mov_b32_e32 v4, v3
	v_cvt_pk_bf16_f32 v96, v6, v7
	v_lshlrev_b32_e32 v6, 16, v15
	v_and_b32_e32 v7, 0xffff0000, v15
	v_mov_b32_e32 v10, v2
	v_pk_mul_f32 v[2:3], v[4:5], v[8:9]
	v_lshrrev_b32_e32 v0, 2, v37
	v_pk_fma_f32 v[2:3], v[10:11], v[6:7], v[2:3] neg_lo:[0,0,1] neg_hi:[0,0,1]
	v_and_or_b32 v0, v0, 3, v133
	v_cvt_pk_bf16_f32 v93, v2, v3
	v_pk_mul_f32 v[2:3], v[10:11], v[8:9]
	v_mul_u32_u24_e32 v144, 0xc0, v0
	v_pk_fma_f32 v[2:3], v[4:5], v[6:7], v[2:3]
	v_and_b32_e32 v0, 16, v37
	v_cvt_pk_bf16_f32 v97, v2, v3
	v_lshlrev_b32_e32 v2, 2, v37
	s_lshr_b32 s13, s30, 6
	v_and_or_b32 v0, v2, 12, v0
	s_add_i32 s30, s30, s31
	v_lshlrev_b32_e32 v145, 1, v0
	v_add_u32_e32 v0, s30, v36
	v_mov_b32_e32 v14, v1
	v_mov_b32_e32 v15, v1
	v_cvt_pk_bf16_f32 v91, v20, v21
	s_waitcnt vmcnt(0)
	v_sub_u32_e32 v146, v0, v133
	v_mov_b32_e32 v0, v1
	v_mov_b32_e32 v2, v1
	v_mov_b32_e32 v3, v1
	v_mov_b32_e32 v4, v1
	v_mov_b32_e32 v5, v1
	v_mov_b32_e32 v6, v1
	v_mov_b32_e32 v7, v1
	v_mov_b32_e32 v8, v1
	v_mov_b32_e32 v9, v1
	v_mov_b32_e32 v10, v1
	v_mov_b32_e32 v11, v1
	v_mov_b32_e32 v12, v1
	v_mov_b32_e32 v13, v1
	v_mov_b64_e32 v[32:33], v[14:15]
	v_cvt_pk_bf16_f32 v92, v16, v17
	v_mov_b64_e32 v[30:31], v[12:13]
	v_mov_b64_e32 v[28:29], v[10:11]
	v_mov_b64_e32 v[26:27], v[8:9]
	v_mov_b64_e32 v[24:25], v[6:7]
	v_mov_b64_e32 v[22:23], v[4:5]
	v_mov_b64_e32 v[20:21], v[2:3]
	v_mov_b64_e32 v[18:19], v[0:1]
	v_mov_b64_e32 v[16:17], v[14:15]
	s_or_b32 s7, s4, 31
	s_or_b32 s14, s13, 3
	v_mul_u32_u24_e32 v143, 0xd0, v36
	s_add_i32 s20, s13, 4
	s_mov_b32 s30, 0
	v_mov_b32_e32 v148, 0xefa18f08
	v_mov_b32_e32 v147, 0
	s_mov_b32 s31, 63
	v_subrev_u32_e32 v66, s26, v66
	v_subrev_u32_e32 v68, s26, v68
	v_subrev_u32_e32 v70, s26, v70
	v_subrev_u32_e32 v72, s26, v72
	s_mov_b32 s42, 0
	v_mov_b64_e32 v[202:203], 0
	v_mov_b64_e32 v[204:205], 0
	v_mov_b64_e32 v[206:207], 0
	v_mov_b64_e32 v[208:209], 0
	v_mov_b64_e32 v[210:211], 0
	v_mov_b64_e32 v[212:213], 0
	v_mov_b64_e32 v[214:215], 0
	v_mov_b64_e32 v[216:217], 0
	v_mov_b64_e32 v[218:219], 0
	v_mov_b64_e32 v[220:221], 0
	v_mov_b64_e32 v[222:223], 0
	v_mov_b64_e32 v[224:225], 0
	v_mov_b64_e32 v[226:227], 0
	v_mov_b64_e32 v[228:229], 0
	v_mov_b64_e32 v[230:231], 0
	v_mov_b64_e32 v[232:233], 0
	v_mov_b64_e32 v[14:15], v[12:13]
	v_mov_b64_e32 v[12:13], v[10:11]
	v_mov_b64_e32 v[10:11], v[8:9]
	v_mov_b64_e32 v[8:9], v[6:7]
	v_mov_b64_e32 v[6:7], v[4:5]
	v_mov_b64_e32 v[4:5], v[2:3]
	v_mov_b64_e32 v[2:3], v[0:1]
	s_waitcnt lgkmcnt(0)
	s_barrier
	s_branch .LBB0_478
